# P1 (in-proj GEMM) sweeps the column tiles in reverse (gates first, x_rnn/g_rnn/qkv last) so the tiles P2 reads are the most recently written; plus the P7 row-panel reversal
# baseline (speedup 1.0000x reference)
.LBB0_253:
	s_cmp_lt_i32 s86, 2
	s_cselect_b64 s[0:1], -1, 0
	s_waitcnt lgkmcnt(0)
	s_add_u32 s48, s84, 0x2600000
	s_addc_u32 s49, s85, 0
	s_add_u32 s52, s84, 0x7600000
	s_addc_u32 s53, s85, 0
	s_add_u32 s2, s84, 0xf600000
	s_addc_u32 s3, s85, 0
	v_writelane_b32 v255, s2, 6
	s_add_u32 s74, s84, 0x15600000
	s_addc_u32 s75, s85, 0
	v_writelane_b32 v255, s3, 7
	s_and_b64 s[2:3], s[0:1], s[10:11]
	v_cndmask_b32_e64 v0, 0, 1, s[2:3]
	v_cmp_ne_u32_e64 s[0:1], 1, v0
	s_andn2_b64 vcc, exec, s[2:3]
	s_cbranch_vccnz .LBB0_279
	s_cmpk_gt_i32 s97, 0xaff
	v_readfirstlane_b32 s9, v251
	s_cbranch_scc1 .LBB0_279
	v_lshrrev_b32_e32 v0, 5, v251
	v_lshrrev_b32_e32 v2, 1, v251
	v_and_b32_e32 v0, 4, v0
	v_bfe_u32 v1, v251, 2, 2
	v_and_b32_e32 v12, 24, v2
	v_lshlrev_b32_e32 v2, 4, v251
	v_or3_b32 v0, v0, v1, v12
	v_add_u32_e32 v1, 0x2000, v2
	v_lshrrev_b32_e32 v3, 7, v1
	s_movk_i32 s4, 0xe0
	v_and_b32_e32 v5, 32, v251
	v_and_or_b32 v4, v3, s4, v0
	v_bitop3_b32 v10, v2, v5, 48 bitop3:0x6c
	v_and_b32_e32 v11, 64, v251
	v_bfe_u32 v13, v251, 2, 4
	s_movk_i32 s4, 0xf0
	v_or_b32_e32 v2, v10, v11
	v_and_or_b32 v3, v3, s4, v13
	s_add_u32 s28, s84, 0x200000
	v_lshl_or_b32 v132, v3, 11, v2
	v_lshrrev_b32_e32 v3, 3, v251
	s_movk_i32 s4, 0x60
	s_addc_u32 s29, s85, 0
	v_and_or_b32 v0, v3, s4, v0
	s_movk_i32 s4, 0x70
	s_ashr_i32 s31, s97, 31
	v_lshl_or_b32 v134, v0, 11, v2
	v_and_or_b32 v0, v3, s4, v13
	s_lshr_b32 s4, s31, 29
	s_add_i32 s4, s97, s4
	s_lshr_b32 s6, s9, 6
	s_ashr_i32 s5, s4, 3
	s_and_b32 s4, s4, -8
	s_lshr_b32 s10, s9, 8
	s_lshl_b32 s30, s6, 10
	s_sub_i32 s4, s97, s4
	s_cmp_lt_i32 s4, 0
	s_movk_i32 s33, 0x161
	s_cselect_b32 s7, s33, 0x160
	s_mul_i32 s4, s4, s7
	s_add_i32 s4, s4, s5
	s_mul_hi_i32 s5, s4, 0x2e8ba2e9
	s_lshr_b32 s7, s5, 31
	s_ashr_i32 s5, s5, 5
	s_add_i32 s5, s5, s7
	s_lshl_b32 s7, s5, 3
	s_mulk_i32 s5, 0xb0
	s_sub_i32 s4, s4, s5
	s_bfe_u32 s5, s4, 0x3001c
	s_add_i32 s5, s4, s5
	s_and_b32 s8, s5, 0xfff8
	s_sub_i32 s4, s4, s8
	s_sext_i32_i16 s4, s4
	s_add_i32 s20, s7, s4
	s_sext_i32_i16 s4, s5
	s_ashr_i32 s21, s20, 31
	s_lshr_b32 s8, s4, 3
	s_sub_i32 s8, 21, s8
	s_lshl_b64 s[4:5], s[20:21], 19
	s_add_u32 s22, s48, s4
	s_addc_u32 s23, s49, s5
	s_bfe_i64 s[4:5], s[8:9], 0x100000
	s_lshl_b64 s[4:5], s[4:5], 19
	s_add_u32 s24, s28, s4
	s_addc_u32 s25, s29, s5
	s_add_i32 s21, s30, 0
	s_add_i32 m0, s21, 0x10000
	v_lshl_or_b32 v130, v4, 11, v2
	global_load_lds_dwordx4 v134, s[24:25]
	s_add_i32 m0, s21, 0x12000
	s_add_u32 s4, s24, 0x40000
	global_load_lds_dwordx4 v130, s[24:25]
	s_addc_u32 s5, s25, 0
	s_add_i32 m0, s21, 0x14000
	s_add_i32 s34, s21, 0x2000
	global_load_lds_dwordx4 v134, s[4:5]
	s_add_i32 m0, s21, 0x16000
	v_lshl_or_b32 v136, v0, 11, v2
	global_load_lds_dwordx4 v130, s[4:5]
	s_mov_b32 m0, s21
	s_add_u32 s4, s22, 0x40000
	global_load_lds_dwordx4 v136, s[22:23]
	s_mov_b32 m0, s34
	s_addc_u32 s5, s23, 0
	s_add_i32 s35, s21, 0x4000
	global_load_lds_dwordx4 v132, s[22:23]
	s_mov_b32 m0, s35
	s_add_i32 s36, s21, 0x6000
	global_load_lds_dwordx4 v136, s[4:5]
	s_mov_b32 m0, s36
	v_mov_b32_e32 v0, 0
	global_load_lds_dwordx4 v132, s[4:5]
	v_mov_b32_e32 v135, v0
	v_mov_b32_e32 v131, v0
	v_mov_b32_e32 v137, v0
	v_mov_b32_e32 v133, v0
	s_cmp_eq_u32 s10, 1
	v_lshl_add_u64 v[8:9], s[24:25], 0, v[134:135]
	v_lshl_add_u64 v[6:7], s[24:25], 0, v[130:131]
	v_lshl_add_u64 v[2:3], s[22:23], 0, v[136:137]
	s_cselect_b64 s[4:5], -1, 0
	s_cmp_lg_u32 s10, 1
	v_lshl_add_u64 v[4:5], s[22:23], 0, v[132:133]
	s_cbranch_scc1 .LBB0_257
	s_barrier

.LBB0_260:
	s_mov_b32 s11, s83
	s_add_i32 s83, s83, 1
	s_cmp_gt_u32 s11, 0x3ffffffe
	s_mov_b64 s[16:17], 0
	s_cbranch_scc1 .LBB0_263
	s_mul_i32 s11, s83, s37
	s_mul_hi_u32 s13, s83, s82
	s_add_i32 s13, s13, s11
	s_mul_i32 s11, s83, s82
	s_add_u32 s14, s11, s97
	s_addc_u32 s15, s13, s31
	v_cmp_gt_i64_e32 vcc, s[14:15], v[142:143]
	s_cbranch_vccnz .LBB0_263
	s_ashr_i32 s10, s14, 31
	s_lshr_b32 s10, s10, 29
	s_add_i32 s10, s14, s10
	s_ashr_i32 s11, s10, 3
	s_and_b32 s10, s10, -8
	s_sub_i32 s10, s14, s10
	s_cmp_lt_i32 s10, 0
	s_cselect_b32 s12, s33, 0x160
	s_mul_i32 s10, s10, s12
	s_add_i32 s10, s10, s11
	s_mul_hi_i32 s11, s10, 0x2e8ba2e9
	s_lshr_b32 s12, s11, 31
	s_ashr_i32 s11, s11, 5
	s_add_i32 s11, s11, s12
	s_lshl_b32 s12, s11, 3
	s_sub_i32 s13, 0x80, s12
	s_min_i32 s13, s13, 8
	s_abs_i32 s14, s13
	v_cvt_f32_u32_e32 v1, s14
	s_sub_i32 s16, 0, s14
	s_mulk_i32 s11, 0xb0
	s_sub_i32 s11, s10, s11
	v_rcp_iflag_f32_e32 v1, v1
	s_abs_i32 s10, s11
	s_xor_b32 s15, s11, s13
	s_ashr_i32 s15, s15, 31
	v_mul_f32_e32 v1, 0x4f7ffffe, v1
	v_cvt_u32_f32_e32 v1, v1
	s_nop 0
	v_readfirstlane_b32 s17, v1
	s_mul_i32 s16, s16, s17
	s_mul_hi_u32 s16, s17, s16
	s_add_i32 s17, s17, s16
	s_mul_hi_u32 s16, s10, s17
	s_mul_i32 s17, s16, s14
	s_sub_i32 s10, s10, s17
	s_add_i32 s18, s16, 1
	s_sub_i32 s17, s10, s14
	s_cmp_ge_u32 s10, s14
	s_cselect_b32 s16, s18, s16
	s_cselect_b32 s10, s17, s10
	s_add_i32 s17, s16, 1
	s_cmp_ge_u32 s10, s14
	s_cselect_b32 s10, s17, s16
	s_xor_b32 s10, s10, s15
	s_sub_i32 s10, s10, s15
	s_mul_i32 s13, s10, s13
	s_sub_i32 s11, s11, s13
	s_add_i32 s12, s12, s11
	s_sub_i32 s10, 21, s10
	s_mov_b64 s[16:17], -1
